# clean config: P0 rewrite (XN, batched item loops, COMB on even waves, rotary prefetch) + P6 relu/non-temporal H stores + attention static priority for waves 0-3 (flips replaced by s_nop)
# speedup vs baseline: 1.0373x; 1.0103x over previous
.LBB0_492:
	ds_read_b128 v[66:69], v197 offset:0
	ds_read_b128 v[70:73], v197 offset:0x4000
	ds_read_b128 v[158:161], v198 offset:0
	ds_read_b128 v[162:165], v198 offset:0x4000
	ds_read_b128 v[166:169], v199 offset:0
	ds_read_b128 v[216:219], v199 offset:0x4000
	s_nop 0
	ds_read_b128 v[220:223], v200 offset:0
	ds_read_b128 v[224:227], v200 offset:0x4000
	s_waitcnt lgkmcnt(6)
	s_waitcnt vmcnt(14)
	v_mfma_f32_32x32x16_bf16 v[82:97], v[66:69], v[98:101], 0
	v_mfma_f32_32x32x16_bf16 v[66:81], v[70:73], v[98:101], 0
	ds_read_b128 v[228:231], v201 offset:0
	ds_read_b128 v[232:235], v201 offset:0x4000
	s_waitcnt lgkmcnt(6)
	s_waitcnt vmcnt(13)
	v_mfma_f32_32x32x16_bf16 v[82:97], v[158:161], v[102:105], v[82:97]
	v_mfma_f32_32x32x16_bf16 v[66:81], v[162:165], v[102:105], v[66:81]
	ds_read_b128 v[158:161], v202 offset:0
	ds_read_b128 v[162:165], v202 offset:0x4000
	s_waitcnt lgkmcnt(6)
	s_waitcnt vmcnt(12)
	v_mfma_f32_32x32x16_bf16 v[82:97], v[166:169], v[106:109], v[82:97]
	v_mfma_f32_32x32x16_bf16 v[66:81], v[216:219], v[106:109], v[66:81]
	ds_read_b128 v[166:169], v204 offset:0
	ds_read_b128 v[216:219], v204 offset:0x4000
	s_waitcnt lgkmcnt(6)
	s_waitcnt vmcnt(11)
	v_mfma_f32_32x32x16_bf16 v[82:97], v[220:223], v[110:113], v[82:97]
	v_mfma_f32_32x32x16_bf16 v[66:81], v[224:227], v[110:113], v[66:81]
	ds_read_b128 v[220:223], v205 offset:0
	ds_read_b128 v[224:227], v205 offset:0x4000
	s_waitcnt lgkmcnt(6)
	s_waitcnt vmcnt(10)
	v_mfma_f32_32x32x16_bf16 v[82:97], v[228:231], v[114:117], v[82:97]
	v_mfma_f32_32x32x16_bf16 v[66:81], v[232:235], v[114:117], v[66:81]
	ds_read_b128 v[228:231], v197 offset:0x100
	ds_read_b128 v[232:235], v197 offset:0x4100
	s_waitcnt lgkmcnt(6)
	s_waitcnt vmcnt(9)
	v_mfma_f32_32x32x16_bf16 v[82:97], v[158:161], v[118:121], v[82:97]
	v_mfma_f32_32x32x16_bf16 v[66:81], v[162:165], v[118:121], v[66:81]
	ds_read_b128 v[158:161], v198 offset:0x100
	ds_read_b128 v[162:165], v198 offset:0x4100
	s_waitcnt lgkmcnt(6)
	s_waitcnt vmcnt(8)
	v_mfma_f32_32x32x16_bf16 v[82:97], v[166:169], v[122:125], v[82:97]
	v_mfma_f32_32x32x16_bf16 v[66:81], v[216:219], v[122:125], v[66:81]
	ds_read_b128 v[166:169], v199 offset:0x100
	ds_read_b128 v[216:219], v199 offset:0x4100
	s_waitcnt lgkmcnt(6)
	s_waitcnt vmcnt(7)
	v_mfma_f32_32x32x16_bf16 v[82:97], v[220:223], v[126:129], v[82:97]
	v_mfma_f32_32x32x16_bf16 v[66:81], v[224:227], v[126:129], v[66:81]
	ds_read_b128 v[220:223], v200 offset:0x100
	ds_read_b128 v[224:227], v200 offset:0x4100
	s_waitcnt lgkmcnt(6)
	s_waitcnt vmcnt(6)
	v_mfma_f32_32x32x16_bf16 v[82:97], v[228:231], v[130:133], v[82:97]
	v_mfma_f32_32x32x16_bf16 v[66:81], v[232:235], v[130:133], v[66:81]
	s_waitcnt lgkmcnt(4)
	s_waitcnt vmcnt(5)
	v_mfma_f32_32x32x16_bf16 v[82:97], v[158:161], v[134:137], v[82:97]
	v_mfma_f32_32x32x16_bf16 v[66:81], v[162:165], v[134:137], v[66:81]
	s_waitcnt lgkmcnt(2)
	s_waitcnt vmcnt(4)
	v_mfma_f32_32x32x16_bf16 v[82:97], v[166:169], v[138:141], v[82:97]
	v_mfma_f32_32x32x16_bf16 v[66:81], v[216:219], v[138:141], v[66:81]
	s_waitcnt lgkmcnt(0)
	s_waitcnt vmcnt(3)
	v_mfma_f32_32x32x16_bf16 v[82:97], v[220:223], v[142:145], v[82:97]
	v_mfma_f32_32x32x16_bf16 v[66:81], v[224:227], v[142:145], v[66:81]
	s_nop 0
	s_sub_i32 s4, s86, 64
	s_cmp_le_i32 s4, s65
	s_cbranch_scc1 .LBB0_494
	v_cmp_gt_u32_e32 vcc, 2.0, v181
	v_add_u32_e32 v0, 0xbfffffe0, v181
	s_nop 4
	v_cndmask_b32_e32 v82, v210, v82, vcc
	v_cmp_lt_u32_e32 vcc, s35, v0
	v_add_u32_e32 v0, 0xbfffffff, v181
	s_nop 0
	v_cndmask_b32_e32 v66, v210, v66, vcc
	v_cmp_lt_u32_e32 vcc, s35, v0
	v_add_u32_e32 v0, 0xbfffffdf, v181
	s_nop 0
	v_cndmask_b32_e32 v83, v210, v83, vcc
	v_cmp_lt_u32_e32 vcc, s35, v0
	v_add_u32_e32 v0, 0xbffffffe, v181
	s_nop 0
	v_cndmask_b32_e32 v67, v210, v67, vcc
	v_cmp_lt_u32_e32 vcc, s35, v0
	v_add_u32_e32 v0, 0xbfffffde, v181
	s_nop 0
	v_cndmask_b32_e32 v84, v210, v84, vcc
	v_cmp_lt_u32_e32 vcc, s35, v0
	v_add_u32_e32 v0, 0xbffffffd, v181
	s_nop 0
	v_cndmask_b32_e32 v68, v210, v68, vcc
	v_cmp_lt_u32_e32 vcc, s35, v0
	v_add_u32_e32 v0, 0xbfffffdd, v181
	s_nop 0
	v_cndmask_b32_e32 v85, v210, v85, vcc
	v_cmp_lt_u32_e32 vcc, s35, v0
	v_add_u32_e32 v0, 0xbffffff8, v181
	s_nop 0
	v_cndmask_b32_e32 v69, v210, v69, vcc
	v_cmp_lt_u32_e32 vcc, s35, v0
	v_add_u32_e32 v0, 0xbfffffd8, v181
	s_nop 0
	v_cndmask_b32_e32 v86, v210, v86, vcc
	v_cmp_lt_u32_e32 vcc, s35, v0
	v_add_u32_e32 v0, 0xbffffff7, v181
	s_nop 0
	v_cndmask_b32_e32 v70, v210, v70, vcc
	v_cmp_lt_u32_e32 vcc, s35, v0
	v_add_u32_e32 v0, 0xbfffffd7, v181
	s_nop 0
	v_cndmask_b32_e32 v87, v210, v87, vcc
	v_cmp_lt_u32_e32 vcc, s35, v0
	v_add_u32_e32 v0, 0xbffffff6, v181
	s_nop 0
	v_cndmask_b32_e32 v71, v210, v71, vcc
	v_cmp_lt_u32_e32 vcc, s35, v0
	v_add_u32_e32 v0, 0xbfffffd6, v181
	s_nop 0
	v_cndmask_b32_e32 v88, v210, v88, vcc
	v_cmp_lt_u32_e32 vcc, s35, v0
	v_add_u32_e32 v0, 0xbffffff5, v181
	s_nop 0
	v_cndmask_b32_e32 v72, v210, v72, vcc
	v_cmp_lt_u32_e32 vcc, s35, v0
	v_add_u32_e32 v0, 0xbfffffd5, v181
	s_nop 0
	v_cndmask_b32_e32 v89, v210, v89, vcc
	v_cmp_lt_u32_e32 vcc, s35, v0
	v_add_u32_e32 v0, 0xbffffff0, v181
	s_nop 0
	v_cndmask_b32_e32 v73, v210, v73, vcc
	v_cmp_lt_u32_e32 vcc, s35, v0
	v_add_u32_e32 v0, 0xbfffffd0, v181
	s_nop 0
	v_cndmask_b32_e32 v90, v210, v90, vcc
	v_cmp_lt_u32_e32 vcc, s35, v0
	v_add_u32_e32 v0, 0xbfffffef, v181
	s_nop 0
	v_cndmask_b32_e32 v74, v210, v74, vcc
	v_cmp_lt_u32_e32 vcc, s35, v0
	v_add_u32_e32 v0, 0xbfffffcf, v181
	s_nop 0
	v_cndmask_b32_e32 v91, v210, v91, vcc
	v_cmp_lt_u32_e32 vcc, s35, v0
	v_add_u32_e32 v0, 0xbfffffee, v181
	s_nop 0
	v_cndmask_b32_e32 v75, v210, v75, vcc
	v_cmp_lt_u32_e32 vcc, s35, v0
	v_add_u32_e32 v0, 0xbfffffce, v181
	s_nop 0
	v_cndmask_b32_e32 v92, v210, v92, vcc
	v_cmp_lt_u32_e32 vcc, s35, v0
	v_add_u32_e32 v0, 0xbfffffed, v181
	s_nop 0
	v_cndmask_b32_e32 v76, v210, v76, vcc
	v_cmp_lt_u32_e32 vcc, s35, v0
	v_add_u32_e32 v0, 0xbfffffcd, v181
	s_nop 0
	v_cndmask_b32_e32 v93, v210, v93, vcc
	v_cmp_lt_u32_e32 vcc, s35, v0
	v_add_u32_e32 v0, 0xbfffffe8, v181
	s_nop 0
	v_cndmask_b32_e32 v77, v210, v77, vcc
	v_cmp_lt_u32_e32 vcc, s35, v0
	v_add_u32_e32 v0, 0xbfffffc8, v181
	s_nop 0
	v_cndmask_b32_e32 v94, v210, v94, vcc
	v_cmp_lt_u32_e32 vcc, s35, v0
	v_add_u32_e32 v0, 0xbfffffe7, v181
	s_nop 0
	v_cndmask_b32_e32 v78, v210, v78, vcc
	v_cmp_lt_u32_e32 vcc, s35, v0
	v_add_u32_e32 v0, 0xbfffffc7, v181
	s_nop 0
	v_cndmask_b32_e32 v95, v210, v95, vcc
	v_cmp_lt_u32_e32 vcc, s35, v0
	v_add_u32_e32 v0, 0xbfffffe6, v181
	s_nop 0
	v_cndmask_b32_e32 v79, v210, v79, vcc
	v_cmp_lt_u32_e32 vcc, s35, v0
	v_add_u32_e32 v0, 0xbfffffc6, v181
	s_nop 0
	v_cndmask_b32_e32 v96, v210, v96, vcc
	v_cmp_lt_u32_e32 vcc, s35, v0
	v_add_u32_e32 v0, 0xbfffffe5, v181
	s_nop 0
	v_cndmask_b32_e32 v80, v210, v80, vcc
	v_cmp_lt_u32_e32 vcc, s35, v0
	v_add_u32_e32 v0, 0xbfffffc5, v181
	s_nop 0
	v_cndmask_b32_e32 v97, v210, v97, vcc
	v_cmp_lt_u32_e32 vcc, s35, v0
	s_nop 1
	v_cndmask_b32_e32 v81, v210, v81, vcc

.LBB0_513:
.LBB0_514:
	s_lshl_b32 s18, s25, 14
	v_add_u32_e32 v0, s18, v195
	ds_read_b64_tr_b16 v[82:83], v0 offset:0
	ds_read_b64_tr_b16 v[84:85], v0 offset:0x800
	ds_read_b64_tr_b16 v[86:87], v0 offset:0x1000
	ds_read_b64_tr_b16 v[88:89], v0 offset:0x1800
	ds_read_b64_tr_b16 v[90:91], v0 offset:0x2000
	ds_read_b64_tr_b16 v[92:93], v0 offset:0x2800
	ds_read_b64_tr_b16 v[94:95], v0 offset:0x3000
	ds_read_b64_tr_b16 v[96:97], v0 offset:0x3800
	ds_read_b64_tr_b16 v[158:159], v0 offset:0x200
	ds_read_b64_tr_b16 v[160:161], v0 offset:0xa00
	ds_read_b64_tr_b16 v[162:163], v0 offset:0x1200
	ds_read_b64_tr_b16 v[164:165], v0 offset:0x1a00
	ds_read_b64_tr_b16 v[166:167], v0 offset:0x2200
	ds_read_b64_tr_b16 v[168:169], v0 offset:0x2a00
	ds_read_b64_tr_b16 v[216:217], v0 offset:0x3200
	ds_read_b64_tr_b16 v[218:219], v0 offset:0x3a00
	s_waitcnt lgkmcnt(8)
	s_mov_b64 s[10:11], -1
	s_nop 0
	v_mfma_f32_32x32x16_bf16 v[50:65], v[66:69], v[82:85], v[50:65]
	v_mfma_f32_32x32x16_bf16 v[50:65], v[70:73], v[86:89], v[50:65]
	v_mfma_f32_32x32x16_bf16 v[50:65], v[74:77], v[90:93], v[50:65]
	v_mfma_f32_32x32x16_bf16 v[50:65], v[78:81], v[94:97], v[50:65]
	ds_read_b64_tr_b16 v[82:83], v0 offset:0x400
	ds_read_b64_tr_b16 v[84:85], v0 offset:0xc00
	ds_read_b64_tr_b16 v[86:87], v0 offset:0x1400
	ds_read_b64_tr_b16 v[88:89], v0 offset:0x1c00
	ds_read_b64_tr_b16 v[90:91], v0 offset:0x2400
	ds_read_b64_tr_b16 v[92:93], v0 offset:0x2c00
	ds_read_b64_tr_b16 v[94:95], v0 offset:0x3400
	ds_read_b64_tr_b16 v[96:97], v0 offset:0x3c00
	s_waitcnt lgkmcnt(8)
	v_mfma_f32_32x32x16_bf16 v[34:49], v[66:69], v[158:161], v[34:49]
	v_mfma_f32_32x32x16_bf16 v[34:49], v[70:73], v[162:165], v[34:49]
	v_mfma_f32_32x32x16_bf16 v[34:49], v[74:77], v[166:169], v[34:49]
	v_mfma_f32_32x32x16_bf16 v[34:49], v[78:81], v[216:219], v[34:49]
	ds_read_b64_tr_b16 v[158:159], v0 offset:0x600
	ds_read_b64_tr_b16 v[160:161], v0 offset:0xe00
	ds_read_b64_tr_b16 v[162:163], v0 offset:0x1600
	ds_read_b64_tr_b16 v[164:165], v0 offset:0x1e00
	ds_read_b64_tr_b16 v[166:167], v0 offset:0x2600
	ds_read_b64_tr_b16 v[168:169], v0 offset:0x2e00
	ds_read_b64_tr_b16 v[216:217], v0 offset:0x3600
	ds_read_b64_tr_b16 v[218:219], v0 offset:0x3e00
	s_waitcnt lgkmcnt(8)
	v_mfma_f32_32x32x16_bf16 v[18:33], v[66:69], v[82:85], v[18:33]
	v_mfma_f32_32x32x16_bf16 v[18:33], v[70:73], v[86:89], v[18:33]
	v_mfma_f32_32x32x16_bf16 v[18:33], v[74:77], v[90:93], v[18:33]
	v_mfma_f32_32x32x16_bf16 v[18:33], v[78:81], v[94:97], v[18:33]
	s_waitcnt lgkmcnt(0)
	v_mfma_f32_32x32x16_bf16 v[2:17], v[66:69], v[158:161], v[2:17]
	v_mfma_f32_32x32x16_bf16 v[2:17], v[70:73], v[162:165], v[2:17]
	v_mfma_f32_32x32x16_bf16 v[2:17], v[74:77], v[166:169], v[2:17]
	v_mfma_f32_32x32x16_bf16 v[2:17], v[78:81], v[216:219], v[2:17]
	s_nop 0
	s_and_b64 vcc, exec, s[36:37]
	s_cbranch_vccz .LBB0_531
	s_andn2_b64 vcc, exec, s[78:79]
	s_cbranch_vccnz .LBB0_521
	s_xor_b64 s[68:69], s[72:73], -1
	s_and_b64 vcc, exec, s[68:69]
	s_cbranch_vccz .LBB0_518
	s_waitcnt vmcnt(0)
	s_mov_b64 s[10:11], 0

.LBB0_533:
	ds_read_b128 v[66:69], v197 offset:0x8000
	ds_read_b128 v[70:73], v197 offset:0xc000
	s_waitcnt vmcnt(1)
	ds_read_b128 v[146:149], v198 offset:0x8000
	ds_read_b128 v[150:153], v198 offset:0xc000
	s_waitcnt vmcnt(0)
	ds_read_b128 v[154:157], v199 offset:0x8000
	ds_read_b128 v[216:219], v199 offset:0xc000
	s_nop 0
	ds_read_b128 v[220:223], v200 offset:0x8000
	ds_read_b128 v[224:227], v200 offset:0xc000
	s_waitcnt lgkmcnt(6)
	v_mfma_f32_32x32x16_bf16 v[82:97], v[66:69], v[98:101], 0
	v_mfma_f32_32x32x16_bf16 v[66:81], v[70:73], v[98:101], 0
	ds_read_b128 v[228:231], v201 offset:0x8000
	ds_read_b128 v[232:235], v201 offset:0xc000
	s_waitcnt lgkmcnt(6)
	v_mfma_f32_32x32x16_bf16 v[82:97], v[146:149], v[102:105], v[82:97]
	v_mfma_f32_32x32x16_bf16 v[66:81], v[150:153], v[102:105], v[66:81]
	ds_read_b128 v[146:149], v202 offset:0x8000
	ds_read_b128 v[150:153], v202 offset:0xc000
	s_waitcnt lgkmcnt(6)
	v_mfma_f32_32x32x16_bf16 v[82:97], v[154:157], v[106:109], v[82:97]
	v_mfma_f32_32x32x16_bf16 v[66:81], v[216:219], v[106:109], v[66:81]
	ds_read_b128 v[154:157], v204 offset:0x8000
	ds_read_b128 v[216:219], v204 offset:0xc000
	s_waitcnt lgkmcnt(6)
	v_mfma_f32_32x32x16_bf16 v[82:97], v[220:223], v[110:113], v[82:97]
	v_mfma_f32_32x32x16_bf16 v[66:81], v[224:227], v[110:113], v[66:81]
	ds_read_b128 v[220:223], v205 offset:0x8000
	ds_read_b128 v[224:227], v205 offset:0xc000
	s_waitcnt lgkmcnt(6)
	v_mfma_f32_32x32x16_bf16 v[82:97], v[228:231], v[114:117], v[82:97]
	v_mfma_f32_32x32x16_bf16 v[66:81], v[232:235], v[114:117], v[66:81]
	ds_read_b128 v[228:231], v197 offset:0x8100
	ds_read_b128 v[232:235], v197 offset:0xc100
	s_waitcnt lgkmcnt(6)
	v_mfma_f32_32x32x16_bf16 v[82:97], v[146:149], v[118:121], v[82:97]
	v_mfma_f32_32x32x16_bf16 v[66:81], v[150:153], v[118:121], v[66:81]
	ds_read_b128 v[146:149], v198 offset:0x8100
	ds_read_b128 v[150:153], v198 offset:0xc100
	s_waitcnt lgkmcnt(6)
	v_mfma_f32_32x32x16_bf16 v[82:97], v[154:157], v[122:125], v[82:97]
	v_mfma_f32_32x32x16_bf16 v[66:81], v[216:219], v[122:125], v[66:81]
	ds_read_b128 v[154:157], v199 offset:0x8100
	ds_read_b128 v[216:219], v199 offset:0xc100
	s_waitcnt lgkmcnt(6)
	v_mfma_f32_32x32x16_bf16 v[82:97], v[220:223], v[126:129], v[82:97]
	v_mfma_f32_32x32x16_bf16 v[66:81], v[224:227], v[126:129], v[66:81]
	ds_read_b128 v[220:223], v200 offset:0x8100
	ds_read_b128 v[224:227], v200 offset:0xc100
	s_waitcnt lgkmcnt(6)
	v_mfma_f32_32x32x16_bf16 v[82:97], v[228:231], v[130:133], v[82:97]
	v_mfma_f32_32x32x16_bf16 v[66:81], v[232:235], v[130:133], v[66:81]
	s_waitcnt lgkmcnt(4)
	v_mfma_f32_32x32x16_bf16 v[82:97], v[146:149], v[134:137], v[82:97]
	v_mfma_f32_32x32x16_bf16 v[66:81], v[150:153], v[134:137], v[66:81]
	s_waitcnt lgkmcnt(2)
	v_mfma_f32_32x32x16_bf16 v[82:97], v[154:157], v[138:141], v[82:97]
	v_mfma_f32_32x32x16_bf16 v[66:81], v[216:219], v[138:141], v[66:81]
	s_waitcnt lgkmcnt(0)
	v_mfma_f32_32x32x16_bf16 v[82:97], v[220:223], v[142:145], v[82:97]
	v_mfma_f32_32x32x16_bf16 v[66:81], v[224:227], v[142:145], v[66:81]
	s_nop 0
	s_cmp_gt_u32 s87, s64
	s_cselect_b64 s[80:81], -1, 0
	s_and_b64 s[10:11], s[48:49], s[80:81]
	s_andn2_b64 vcc, exec, s[10:11]
	s_mov_b64 s[72:73], s[84:85]
	s_cbranch_vccnz .LBB0_535
	global_load_dwordx4 v[98:101], v[186:187], off
	global_load_dwordx4 v[102:105], v[186:187], off offset:32
	global_load_dwordx4 v[106:109], v[186:187], off offset:64
	global_load_dwordx4 v[110:113], v[186:187], off offset:96
	global_load_dwordx4 v[114:117], v[186:187], off offset:128
	global_load_dwordx4 v[118:121], v[186:187], off offset:160
	global_load_dwordx4 v[122:125], v[186:187], off offset:192
	global_load_dwordx4 v[126:129], v[186:187], off offset:224
	global_load_dwordx4 v[130:133], v[186:187], off offset:256
	global_load_dwordx4 v[134:137], v[186:187], off offset:288
	global_load_dwordx4 v[138:141], v[186:187], off offset:320
	global_load_dwordx4 v[142:145], v[186:187], off offset:352
	s_mov_b64 s[72:73], -1

.LBB0_556:
.LBB0_557:
	s_lshl_b32 s10, s25, 14
	v_add_u32_e32 v0, s10, v195
	ds_read_b64_tr_b16 v[82:83], v0 offset:0
	ds_read_b64_tr_b16 v[84:85], v0 offset:0x800
	ds_read_b64_tr_b16 v[90:91], v0 offset:0x1000
	ds_read_b64_tr_b16 v[92:93], v0 offset:0x1800
	ds_read_b64_tr_b16 v[94:95], v0 offset:0x2000
	ds_read_b64_tr_b16 v[96:97], v0 offset:0x2800
	ds_read_b64_tr_b16 v[146:147], v0 offset:0x3000
	ds_read_b64_tr_b16 v[148:149], v0 offset:0x3800
	ds_read_b64_tr_b16 v[150:151], v0 offset:0x200
	ds_read_b64_tr_b16 v[152:153], v0 offset:0xa00
	ds_read_b64_tr_b16 v[154:155], v0 offset:0x1200
	ds_read_b64_tr_b16 v[156:157], v0 offset:0x1a00
	ds_read_b64_tr_b16 v[218:219], v0 offset:0x2200
	ds_read_b64_tr_b16 v[220:221], v0 offset:0x2a00
	ds_read_b64_tr_b16 v[222:223], v0 offset:0x3200
	ds_read_b64_tr_b16 v[224:225], v0 offset:0x3a00
	s_waitcnt lgkmcnt(8)
	s_nop 0
	v_mfma_f32_32x32x16_bf16 v[50:65], v[66:69], v[82:85], v[50:65]
	v_mfma_f32_32x32x16_bf16 v[50:65], v[70:73], v[90:93], v[50:65]
	v_mfma_f32_32x32x16_bf16 v[50:65], v[74:77], v[94:97], v[50:65]
	v_mfma_f32_32x32x16_bf16 v[50:65], v[78:81], v[146:149], v[50:65]
	ds_read_b64_tr_b16 v[82:83], v0 offset:0x400
	ds_read_b64_tr_b16 v[84:85], v0 offset:0xc00
	ds_read_b64_tr_b16 v[90:91], v0 offset:0x1400
	ds_read_b64_tr_b16 v[92:93], v0 offset:0x1c00
	ds_read_b64_tr_b16 v[94:95], v0 offset:0x2400
	ds_read_b64_tr_b16 v[96:97], v0 offset:0x2c00
	ds_read_b64_tr_b16 v[146:147], v0 offset:0x3400
	ds_read_b64_tr_b16 v[148:149], v0 offset:0x3c00
	s_waitcnt lgkmcnt(8)
	v_mfma_f32_32x32x16_bf16 v[34:49], v[66:69], v[150:153], v[34:49]
	v_mfma_f32_32x32x16_bf16 v[34:49], v[70:73], v[154:157], v[34:49]
	v_mfma_f32_32x32x16_bf16 v[34:49], v[74:77], v[218:221], v[34:49]
	v_mfma_f32_32x32x16_bf16 v[34:49], v[78:81], v[222:225], v[34:49]
	ds_read_b64_tr_b16 v[150:151], v0 offset:0x600
	ds_read_b64_tr_b16 v[152:153], v0 offset:0xe00
	ds_read_b64_tr_b16 v[154:155], v0 offset:0x1600
	ds_read_b64_tr_b16 v[156:157], v0 offset:0x1e00
	ds_read_b64_tr_b16 v[218:219], v0 offset:0x2600
	ds_read_b64_tr_b16 v[220:221], v0 offset:0x2e00
	ds_read_b64_tr_b16 v[222:223], v0 offset:0x3600
	ds_read_b64_tr_b16 v[224:225], v0 offset:0x3e00
	s_waitcnt lgkmcnt(8)
	v_mfma_f32_32x32x16_bf16 v[18:33], v[66:69], v[82:85], v[18:33]
	v_mfma_f32_32x32x16_bf16 v[18:33], v[70:73], v[90:93], v[18:33]
	v_mfma_f32_32x32x16_bf16 v[18:33], v[74:77], v[94:97], v[18:33]
	v_mfma_f32_32x32x16_bf16 v[18:33], v[78:81], v[146:149], v[18:33]
	s_waitcnt lgkmcnt(0)
	v_mfma_f32_32x32x16_bf16 v[2:17], v[66:69], v[150:153], v[2:17]
	v_mfma_f32_32x32x16_bf16 v[2:17], v[70:73], v[154:157], v[2:17]
	v_mfma_f32_32x32x16_bf16 v[2:17], v[74:77], v[218:221], v[2:17]
	v_mfma_f32_32x32x16_bf16 v[2:17], v[78:81], v[222:225], v[2:17]
	s_nop 0
	s_andn2_b64 vcc, exec, s[36:37]
	s_cbranch_vccnz .LBB0_567
	s_andn2_b64 vcc, exec, s[82:83]
	s_cbranch_vccnz .LBB0_564
	s_xor_b64 s[18:19], s[72:73], -1
	s_mov_b64 s[4:5], -1
	s_and_b64 vcc, exec, s[18:19]
	s_cbranch_vccz .LBB0_561
	s_waitcnt vmcnt(0)
	s_mov_b64 s[4:5], 0

.LBB0_965:
	v_lshl_add_u32 v22, s76, 8, v152
	v_lshl_or_b32 v20, s77, 8, v154
	v_ashrrev_i32_e32 v23, 31, v22
	v_ashrrev_i32_e32 v21, 31, v20
	v_lshlrev_b64 v[158:159], 13, v[22:23]
	v_pk_mul_f32 v[38:39], v[126:127], v[126:127]
	v_pk_mul_f32 v[36:37], v[124:125], v[124:125]
	v_pk_mul_f32 v[122:123], v[122:123], v[122:123]
	v_pk_mul_f32 v[120:121], v[120:121], v[120:121]
	v_cvt_pk_bf16_f32 v36, v36, v37
	v_cvt_pk_bf16_f32 v37, v38, v39
	v_cvt_pk_bf16_f32 v38, v120, v121
	v_cvt_pk_bf16_f32 v39, v122, v123
	v_lshl_add_u64 v[120:121], s[30:31], 0, v[158:159]
	v_lshlrev_b64 v[122:123], 1, v[20:21]
	v_lshl_add_u64 v[20:21], v[120:121], 0, v[122:123]
	global_store_dwordx4 v[20:21], v[36:39], off nt
	v_pk_mul_f32 v[120:121], v[150:151], v[150:151]
	v_pk_mul_f32 v[124:125], v[148:149], v[148:149]
	v_pk_mul_f32 v[38:39], v[146:147], v[146:147]
	v_pk_mul_f32 v[36:37], v[144:145], v[144:145]
	v_pk_mul_f32 v[66:67], v[66:67], v[66:67]
	v_cvt_pk_bf16_f32 v36, v36, v37
	v_cvt_pk_bf16_f32 v37, v38, v39
	v_cvt_pk_bf16_f32 v38, v124, v125
	v_cvt_pk_bf16_f32 v39, v120, v121
	global_store_dwordx4 v[20:21], v[36:39], off offset:256 nt
	v_pk_mul_f32 v[64:65], v[64:65], v[64:65]
	v_pk_mul_f32 v[58:59], v[58:59], v[58:59]
	v_or_b32_e32 v36, 16, v22
	v_ashrrev_i32_e32 v37, 31, v36
	v_lshlrev_b64 v[120:121], 13, v[36:37]
	v_pk_mul_f32 v[38:39], v[106:107], v[106:107]
	v_pk_mul_f32 v[36:37], v[104:105], v[104:105]
	v_pk_mul_f32 v[104:105], v[110:111], v[110:111]
	v_pk_mul_f32 v[106:107], v[108:109], v[108:109]
	v_cvt_pk_bf16_f32 v36, v36, v37
	v_cvt_pk_bf16_f32 v37, v38, v39
	v_cvt_pk_bf16_f32 v39, v104, v105
	v_lshl_add_u64 v[104:105], s[30:31], 0, v[120:121]
	v_cvt_pk_bf16_f32 v38, v106, v107
	v_lshl_add_u64 v[104:105], v[104:105], 0, v[122:123]
	global_store_dwordx4 v[104:105], v[36:39], off nt
	v_pk_mul_f32 v[106:107], v[118:119], v[118:119]
	v_pk_mul_f32 v[108:109], v[116:117], v[116:117]
	v_pk_mul_f32 v[38:39], v[114:115], v[114:115]
	v_pk_mul_f32 v[36:37], v[112:113], v[112:113]
	v_pk_mul_f32 v[10:11], v[10:11], v[10:11]
	v_cvt_pk_bf16_f32 v36, v36, v37
	v_cvt_pk_bf16_f32 v37, v38, v39
	v_cvt_pk_bf16_f32 v38, v108, v109
	v_cvt_pk_bf16_f32 v39, v106, v107
	global_store_dwordx4 v[104:105], v[36:39], off offset:256 nt
	v_pk_mul_f32 v[8:9], v[8:9], v[8:9]
	v_pk_mul_f32 v[14:15], v[14:15], v[14:15]
	v_or_b32_e32 v36, 32, v22
	v_ashrrev_i32_e32 v37, 31, v36
	v_lshlrev_b64 v[104:105], 13, v[36:37]
	v_pk_mul_f32 v[38:39], v[90:91], v[90:91]
	v_pk_mul_f32 v[36:37], v[88:89], v[88:89]
	v_pk_mul_f32 v[88:89], v[94:95], v[94:95]
	v_pk_mul_f32 v[90:91], v[92:93], v[92:93]
	v_cvt_pk_bf16_f32 v36, v36, v37
	v_cvt_pk_bf16_f32 v37, v38, v39
	v_cvt_pk_bf16_f32 v39, v88, v89
	v_lshl_add_u64 v[88:89], s[30:31], 0, v[104:105]
	v_cvt_pk_bf16_f32 v38, v90, v91
	v_lshl_add_u64 v[88:89], v[88:89], 0, v[122:123]
	v_or_b32_e32 v22, 48, v22
	global_store_dwordx4 v[88:89], v[36:39], off nt
	v_ashrrev_i32_e32 v23, 31, v22
	v_lshlrev_b64 v[22:23], 13, v[22:23]
	v_pk_mul_f32 v[38:39], v[82:83], v[82:83]
	v_pk_mul_f32 v[36:37], v[80:81], v[80:81]
	v_pk_mul_f32 v[80:81], v[98:99], v[98:99]
	v_pk_mul_f32 v[82:83], v[96:97], v[96:97]
	v_cvt_pk_bf16_f32 v36, v36, v37
	v_cvt_pk_bf16_f32 v37, v38, v39
	v_cvt_pk_bf16_f32 v38, v82, v83
	v_cvt_pk_bf16_f32 v39, v80, v81
	global_store_dwordx4 v[88:89], v[36:39], off offset:256 nt
	v_lshl_add_u64 v[22:23], s[30:31], 0, v[22:23]
	v_lshl_add_u64 v[22:23], v[22:23], 0, v[122:123]
	v_pk_mul_f32 v[38:39], v[74:75], v[74:75]
	v_pk_mul_f32 v[36:37], v[72:73], v[72:73]
	v_pk_mul_f32 v[72:73], v[78:79], v[78:79]
	v_pk_mul_f32 v[74:75], v[76:77], v[76:77]
	v_cvt_pk_bf16_f32 v36, v36, v37
	v_cvt_pk_bf16_f32 v37, v38, v39
	v_cvt_pk_bf16_f32 v38, v74, v75
	v_cvt_pk_bf16_f32 v39, v72, v73
	global_store_dwordx4 v[22:23], v[36:39], off nt
	v_pk_mul_f32 v[26:27], v[26:27], v[26:27]
	v_pk_mul_f32 v[30:31], v[30:31], v[30:31]
	v_pk_mul_f32 v[38:39], v[70:71], v[70:71]
	v_pk_mul_f32 v[36:37], v[68:69], v[68:69]
	v_pk_mul_f32 v[12:13], v[12:13], v[12:13]
	v_cvt_pk_bf16_f32 v36, v36, v37
	v_cvt_pk_bf16_f32 v37, v38, v39
	v_cvt_pk_bf16_f32 v38, v64, v65
	v_cvt_pk_bf16_f32 v39, v66, v67
	global_store_dwordx4 v[22:23], v[36:39], off offset:256 nt
	v_pk_mul_f32 v[22:23], v[62:63], v[62:63]
	v_cvt_pk_bf16_f32 v8, v8, v9
	v_pk_mul_f32 v[36:37], v[60:61], v[60:61]
	v_pk_mul_f32 v[38:39], v[56:57], v[56:57]
	v_add_co_u32_e32 v56, vcc, s70, v20
	v_cvt_pk_bf16_f32 v36, v36, v37
	v_cvt_pk_bf16_f32 v37, v22, v23
	v_cvt_pk_bf16_f32 v38, v38, v39
	v_cvt_pk_bf16_f32 v39, v58, v59
	v_addc_co_u32_e32 v57, vcc, 0, v21, vcc
	global_store_dwordx4 v[56:57], v[36:39], off nt
	v_pk_mul_f32 v[56:57], v[102:103], v[102:103]
	v_pk_mul_f32 v[58:59], v[100:101], v[100:101]
	v_pk_mul_f32 v[38:39], v[86:87], v[86:87]
	v_pk_mul_f32 v[36:37], v[84:85], v[84:85]
	v_lshl_add_u64 v[22:23], v[20:21], 0, s[36:37]
	v_cvt_pk_bf16_f32 v36, v36, v37
	v_cvt_pk_bf16_f32 v37, v38, v39
	v_cvt_pk_bf16_f32 v38, v58, v59
	v_cvt_pk_bf16_f32 v39, v56, v57
	global_store_dwordx4 v[22:23], v[36:39], off offset:256 nt
	v_pk_mul_f32 v[22:23], v[42:43], v[42:43]
	v_pk_mul_f32 v[42:43], v[52:53], v[52:53]
	v_pk_mul_f32 v[36:37], v[40:41], v[40:41]
	v_pk_mul_f32 v[40:41], v[46:47], v[46:47]
	v_pk_mul_f32 v[38:39], v[44:45], v[44:45]
	v_cvt_pk_bf16_f32 v36, v36, v37
	v_cvt_pk_bf16_f32 v38, v38, v39
	v_cvt_pk_bf16_f32 v39, v40, v41
	v_add_co_u32_e32 v40, vcc, s71, v20
	v_cvt_pk_bf16_f32 v37, v22, v23
	s_nop 0
	v_addc_co_u32_e32 v41, vcc, 0, v21, vcc
	global_store_dwordx4 v[40:41], v[36:39], off nt
	v_pk_mul_f32 v[40:41], v[54:55], v[54:55]
	v_lshl_add_u64 v[22:23], v[20:21], 0, s[38:39]
	v_pk_mul_f32 v[38:39], v[50:51], v[50:51]
	v_pk_mul_f32 v[36:37], v[48:49], v[48:49]
	v_cvt_pk_bf16_f32 v9, v10, v11
	v_cvt_pk_bf16_f32 v36, v36, v37
	v_cvt_pk_bf16_f32 v37, v38, v39
	v_cvt_pk_bf16_f32 v38, v42, v43
	v_cvt_pk_bf16_f32 v39, v40, v41
	global_store_dwordx4 v[22:23], v[36:39], off offset:256 nt
	v_pk_mul_f32 v[22:23], v[24:25], v[24:25]
	v_pk_mul_f32 v[24:25], v[28:29], v[28:29]
	v_add_co_u32_e32 v28, vcc, s72, v20
	v_cvt_pk_bf16_f32 v11, v14, v15
	s_nop 0
	v_addc_co_u32_e32 v29, vcc, 0, v21, vcc
	v_add_co_u32_e32 v14, vcc, s73, v20
	v_cvt_pk_bf16_f32 v22, v22, v23
	v_cvt_pk_bf16_f32 v23, v26, v27
	v_cvt_pk_bf16_f32 v24, v24, v25
	v_cvt_pk_bf16_f32 v25, v30, v31
	v_cvt_pk_bf16_f32 v10, v12, v13
	v_addc_co_u32_e32 v15, vcc, 0, v21, vcc
	global_store_dwordx4 v[28:29], v[22:25], off nt
	v_pk_mul_f32 v[18:19], v[18:19], v[18:19]
	v_pk_mul_f32 v[16:17], v[16:17], v[16:17]
	v_pk_mul_f32 v[22:23], v[34:35], v[34:35]
	v_pk_mul_f32 v[24:25], v[32:33], v[32:33]
	global_store_dwordx4 v[14:15], v[8:11], off nt
	v_pk_mul_f32 v[6:7], v[6:7], v[6:7]
	v_pk_mul_f32 v[4:5], v[4:5], v[4:5]
	v_pk_mul_f32 v[8:9], v[2:3], v[2:3]
	v_pk_mul_f32 v[2:3], v[0:1], v[0:1]
	v_lshl_add_u64 v[26:27], v[20:21], 0, s[40:41]
	v_cvt_pk_bf16_f32 v16, v16, v17
	v_cvt_pk_bf16_f32 v17, v18, v19
	v_cvt_pk_bf16_f32 v18, v24, v25
	v_cvt_pk_bf16_f32 v19, v22, v23
	v_lshl_add_u64 v[12:13], v[20:21], 0, s[42:43]
	v_cvt_pk_bf16_f32 v0, v4, v5
	v_cvt_pk_bf16_f32 v1, v6, v7
	v_cvt_pk_bf16_f32 v2, v2, v3
	v_cvt_pk_bf16_f32 v3, v8, v9
	s_and_b64 vcc, exec, s[0:1]
	s_mov_b64 s[0:1], -1
	global_store_dwordx4 v[26:27], v[16:19], off offset:256 nt
	global_store_dwordx4 v[12:13], v[0:3], off offset:256 nt
	s_cbranch_vccnz .LBB0_948
	s_andn2_b64 vcc, exec, s[20:21]
	s_cbranch_vccnz .LBB0_947
	s_barrier
	s_branch .LBB0_947
